# plus A-loop middle PV group: three more V^T reads issued early into the free quads, counted lgkmcnt
# baseline (speedup 1.0000x reference)
; DI void qk_tile(f32x4 (&st)[4], const char* sK, const bf16x8 (&qf)[2], int lr, int g) {
; #pragma unroll
;   for (int kt = 0; kt < 4; ++kt) {
;     st[kt] = (f32x4){0.f, 0.f, 0.f, 0.f};
; #pragma unroll
;     for (int ks = 0; ks < 2; ++ks) st[kt] = MFMA16(*(const bf16x8*)(sK + (kt * 16 + lr) * 128 + (((ks * 4 + g) ^ ((lr >> 1) & 7)) << 4)), qf[ks], st[kt]);
;   }
; }
; DI void qk_tile2(f32x4 (&sa)[4], f32x4 (&sb)[4], const char* sK, const bf16x8 (&qa)[2], const bf16x8 (&qb)[2], int lr, int g) {
; #pragma unroll
;   for (int kt = 0; kt < 4; ++kt) {
;     const bf16x8 k0 = *(const bf16x8*)(sK + (kt * 16 + lr) * 128 + ((g ^ ((lr >> 1) & 7)) << 4)), k1 = *(const bf16x8*)(sK + (kt * 16 + lr) * 128 + (((4 + g) ^ ((lr >> 1) & 7)) << 4));
;     sa[kt] = MFMA16(k0, qa[0], ((f32x4){0.f, 0.f, 0.f, 0.f})); sb[kt] = MFMA16(k0, qb[0], ((f32x4){0.f, 0.f, 0.f, 0.f}));
;     sa[kt] = MFMA16(k1, qa[1], sa[kt]); sb[kt] = MFMA16(k1, qb[1], sb[kt]);
;   }
; }
; DI float softmax_step(f32x4 (&st)[4], float& m, float& lsum) {
;   float mx = fmaxf(fmaxf(fmaxf(st[0][0], st[0][1]), fmaxf(st[0][2], st[0][3])), fmaxf(fmaxf(st[1][0], st[1][1]), fmaxf(st[1][2], st[1][3])));
;   mx = fmaxf(mx, fmaxf(fmaxf(fmaxf(st[2][0], st[2][1]), fmaxf(st[2][2], st[2][3])), fmaxf(fmaxf(st[3][0], st[3][1]), fmaxf(st[3][2], st[3][3]))));
;   mx = fmaxf(mx, __shfl_xor(mx, 16)); mx = fmaxf(mx, __shfl_xor(mx, 32));
;   const float mn = fmaxf(m, mx);
;   const float mu = mn == -INFINITY ? 0.f : mn;
;   const float alpha = __builtin_amdgcn_exp2f(m - mu);
;   float ps = 0.f;
; #pragma unroll
;   for (int kt = 0; kt < 4; ++kt)
; #pragma unroll
;     for (int j = 0; j < 4; ++j) { const float p = __builtin_amdgcn_exp2f(st[kt][j] - mu); st[kt][j] = p; ps += p; }
;   lsum = lsum * alpha + ps; m = mn;
;   return alpha;
; }
; DI void attn_A(const Params& P, int l, int b, int head, int qt, float lam, char* smem, bf16_t* ybase, size_t ypitch) {
;     ...
;   for (int n = 0; n <= qt; ++n) {
;     const char* sb = smem + (n & 1) * STAGE;
;     if (n < qt) {
;       const bf16_t* kn = kbase + (size_t)(n + 1) * 64 * PW;
;       gload2(rk0, kn, PW, tid); gload2(rk1, kn + 64, PW, tid); gload4(rv, vbase + (n + 1) * 64, SEQ, tid);
;     }
;     f32x4 s0[4], s1[4];
;     qk_tile(s0, sb, qf0, lr, g);
;     qk_tile(s1, sb + 9216, qf1, lr, g);
;     const float a0 = softmax_step(s0, m0, l0), a1 = softmax_step(s1, m1, l1);
.LBB0_810:
	s_bitcmp1_b32 s8, 0
	s_cselect_b32 s9, 0x9000, 0
	v_or_b32_e32 v120, s9, v199
	v_add_u32_e32 v219, v120, v200
	v_add_u32_e32 v202, v120, v201
	ds_read_b128 v[112:115], v219
	ds_read_b128 v[116:119], v219 offset:2048
	ds_read_b128 v[120:123], v202
	ds_read_b128 v[124:127], v202 offset:2048
	s_waitcnt lgkmcnt(3)
	v_mfma_f32_16x16x32_f16 v[112:115], v[112:115], v[0:3], 0
	s_mov_b32 s9, 0xff800000
	s_waitcnt lgkmcnt(1)
	v_mfma_f32_16x16x32_f16 v[136:139], v[120:123], v[8:11], v[112:115]
	s_nop 4
	ds_read_b128 v[112:115], v219 offset:4096
	ds_read_b128 v[120:123], v202 offset:4096
	v_mfma_f32_16x16x32_f16 v[116:119], v[116:119], v[0:3], 0
	s_waitcnt lgkmcnt(1)
	v_mfma_f32_16x16x32_f16 v[112:115], v[112:115], v[0:3], 0
	v_mfma_f32_16x16x32_f16 v[128:131], v[124:127], v[8:11], v[116:119]
	s_nop 4
	ds_read_b128 v[116:119], v219 offset:6144
	ds_read_b128 v[140:143], v219 offset:9216
	ds_read_b128 v[124:127], v202 offset:6144
	ds_read_b128 v[144:147], v202 offset:9216
	ds_read_b128 v[204:207], v219 offset:11264
	ds_read_b128 v[210:213], v219 offset:13312
	s_waitcnt lgkmcnt(6)
	v_mfma_f32_16x16x32_f16 v[132:135], v[120:123], v[8:11], v[112:115]
	ds_read_b128 v[120:123], v202 offset:11264
	ds_read_b128 v[220:223], v202 offset:13312
	ds_read_b128 v[224:227], v219 offset:15360
	s_waitcnt lgkmcnt(8)
	v_mfma_f32_16x16x32_f16 v[112:115], v[116:119], v[0:3], 0
	v_max_f32_e32 v116, v138, v139
	v_max3_f32 v203, v136, v137, v116
	v_max_f32_e32 v116, v130, v131
	s_waitcnt lgkmcnt(6)
	v_mfma_f32_16x16x32_f16 v[124:127], v[124:127], v[8:11], v[112:115]
	v_mfma_f32_16x16x32_f16 v[112:115], v[140:143], v[4:7], 0
	v_max3_f32 v140, v128, v129, v116
	v_max_f32_e32 v141, v132, v133
	s_waitcnt lgkmcnt(4)
	v_mfma_f32_16x16x32_f16 v[116:119], v[204:207], v[4:7], 0
	v_max_f32_e32 v142, v134, v135
	s_waitcnt lgkmcnt(2)
	v_mfma_f32_16x16x32_f16 v[116:119], v[120:123], v[12:15], v[116:119]
	v_max_f32_e32 v120, v126, v127
	v_max3_f32 v143, v124, v125, v120
	v_max3_f32 v141, v141, v142, v143
	v_mfma_f32_16x16x32_f16 v[112:115], v[144:147], v[12:15], v[112:115]
	v_max3_f32 v144, v203, v140, v141
	ds_bpermute_b32 v145, v189, v144
	ds_read_b128 v[140:143], v202 offset:15360
	v_mfma_f32_16x16x32_f16 v[120:123], v[210:213], v[4:7], 0
	s_waitcnt lgkmcnt(1)
	v_max_f32_e32 v203, v144, v145
	ds_bpermute_b32 v204, v188, v203
	v_mfma_f32_16x16x32_f16 v[144:147], v[224:227], v[4:7], 0
	s_waitcnt lgkmcnt(1)
	v_mfma_f32_16x16x32_f16 v[232:235], v[140:143], v[12:15], v[144:147]
	v_mfma_f32_16x16x32_f16 v[120:123], v[220:223], v[12:15], v[120:123]
	s_waitcnt lgkmcnt(0)
	s_nop 3
	v_max3_f32 v146, v209, v203, v204
	v_cmp_neq_f32_e32 vcc, s9, v146
	ds_read_b128 v[220:223], v219 offset:32768
	ds_read_b128 v[224:227], v219 offset:18432
	ds_read_b128 v[228:231], v202 offset:18432
	v_cndmask_b32_e32 v141, 0, v146, vcc
	v_sub_f32_e32 v136, v136, v141
	v_sub_f32_e32 v128, v128, v141
	v_exp_f32_e32 v203, v136
	v_sub_f32_e32 v136, v137, v141
	v_exp_f32_e32 v207, v128
	v_sub_f32_e32 v128, v129, v141
	v_sub_f32_e32 v129, v131, v141
	v_exp_f32_e32 v204, v136
	v_sub_f32_e32 v136, v138, v141
	v_exp_f32_e32 v208, v128
	v_sub_f32_e32 v128, v130, v141
	v_exp_f32_e32 v130, v129
	v_sub_f32_e32 v129, v132, v141
	v_exp_f32_e32 v205, v136
	v_sub_f32_e32 v136, v139, v141
	v_exp_f32_e32 v132, v129
	v_sub_f32_e32 v129, v133, v141
	v_exp_f32_e32 v206, v136
	v_exp_f32_e32 v136, v129
	v_sub_f32_e32 v129, v134, v141
	v_exp_f32_e32 v134, v129
	v_sub_f32_e32 v129, v135, v141
	v_exp_f32_e32 v138, v129
	v_max_f32_e32 v129, v114, v115
	v_max_f32_e32 v131, v118, v119
	v_max_f32_e32 v133, v120, v121
	v_max_f32_e32 v135, v122, v123
	v_max_f32_e32 v137, v234, v235
	v_max3_f32 v137, v232, v233, v137
	v_max3_f32 v129, v112, v113, v129
	v_max3_f32 v131, v116, v117, v131
	v_max3_f32 v133, v133, v135, v137
	v_max3_f32 v129, v129, v131, v133
	v_mov_b32_e32 v131, v129
	v_sub_f32_e32 v125, v125, v141
	v_exp_f32_e32 v140, v125
	v_sub_f32_e32 v125, v126, v141
	v_exp_f32_e32 v126, v125
	s_waitcnt lgkmcnt(0)
	s_nop 1
	v_permlane16_swap_b32_e32 v129, v131
	v_max_f32_e32 v125, v129, v131
	v_mov_b32_e32 v129, v125
	v_sub_f32_e32 v127, v127, v141
	v_exp_f32_e32 v142, v127
	v_sub_f32_e32 v127, v209, v141
	v_exp_f32_e32 v128, v128
	s_waitcnt lgkmcnt(0)
; #define MFMA16(a, b, c) __builtin_amdgcn_mfma_f32_16x16x32_f16((a), (b), (c), 0, 0, 0)
; DI float softmax_step(f32x4 (&st)[4], float& m, float& lsum) {
;   float mx = fmaxf(fmaxf(fmaxf(st[0][0], st[0][1]), fmaxf(st[0][2], st[0][3])), fmaxf(fmaxf(st[1][0], st[1][1]), fmaxf(st[1][2], st[1][3])));
;   mx = fmaxf(mx, fmaxf(fmaxf(fmaxf(st[2][0], st[2][1]), fmaxf(st[2][2], st[2][3])), fmaxf(fmaxf(st[3][0], st[3][1]), fmaxf(st[3][2], st[3][3]))));
;   mx = fmaxf(mx, __shfl_xor(mx, 16)); mx = fmaxf(mx, __shfl_xor(mx, 32));
;   const float mn = fmaxf(m, mx);
;   const float mu = mn == -INFINITY ? 0.f : mn;
;   const float alpha = __builtin_amdgcn_exp2f(m - mu);
;   float ps = 0.f;
; #pragma unroll
;   for (int kt = 0; kt < 4; ++kt)
; #pragma unroll
;     for (int j = 0; j < 4; ++j) { const float p = __builtin_amdgcn_exp2f(st[kt][j] - mu); st[kt][j] = p; ps += p; }
;   lsum = lsum * alpha + ps; m = mn;
;   return alpha;
; }
; DI void attn_A(const Params& P, int l, int b, int head, int qt, float lam, char* smem, bf16_t* ybase, size_t ypitch) {
;     ...
;     const float a0 = softmax_step(s0, m0, l0), a1 = softmax_step(s1, m1, l1);
; #pragma unroll
;     for (int i = 0; i < 8; ++i) { o0[i] *= a0; o1[i] *= a1; }
; #pragma unroll
;     for (int kk = 0; kk < 2; ++kk) {
;       const bf16x8 p0 = pack8(s0[2 * kk], s0[2 * kk + 1]), p1 = pack8(s1[2 * kk], s1[2 * kk + 1]);
; #pragma unroll
;       for (int dt = 0; dt < 8; ++dt) {
;         const bf16x8 vf = vfrag(sb + 18432, dt, kk, lr, g);
;         o0[dt] = MFMA16(vf, p0, o0[dt]);
;         o1[dt] = MFMA16(vf, p1, o1[dt]);
;       }
;     }
	s_nop 1
	v_permlane32_swap_b32_e32 v125, v129
	v_max3_f32 v147, v215, v125, v129
	v_cmp_neq_f32_e32 vcc, s9, v147
	v_exp_f32_e32 v144, v127
	ds_read_b128 v[236:239], v219 offset:20480
	v_cndmask_b32_e32 v143, 0, v147, vcc
	v_sub_f32_e32 v112, v112, v143
	v_exp_f32_e32 v209, v112
	v_sub_f32_e32 v112, v113, v143
	v_exp_f32_e32 v210, v112
	v_sub_f32_e32 v112, v114, v143
	v_exp_f32_e32 v211, v112
	v_sub_f32_e32 v112, v115, v143
	v_exp_f32_e32 v212, v112
	v_sub_f32_e32 v112, v116, v143
	v_exp_f32_e32 v213, v112
	v_sub_f32_e32 v112, v117, v143
	v_exp_f32_e32 v214, v112
	v_sub_f32_e32 v112, v118, v143
	v_exp_f32_e32 v129, v112
	v_sub_f32_e32 v112, v119, v143
	v_exp_f32_e32 v131, v112
	v_sub_f32_e32 v112, v120, v143
	v_exp_f32_e32 v133, v112
	v_sub_f32_e32 v112, v121, v143
	v_exp_f32_e32 v137, v112
	v_sub_f32_e32 v112, v122, v143
	v_exp_f32_e32 v135, v112
	v_sub_f32_e32 v112, v215, v143
	v_exp_f32_e32 v120, v112
	v_sub_f32_e32 v121, v123, v143
	v_cvt_pk_f16_f32 v112, v203, v204
	v_cvt_pk_f16_f32 v113, v205, v206
	v_cvt_pk_f16_f32 v114, v207, v208
	v_cvt_pk_f16_f32 v116, v209, v210
	v_cvt_pk_f16_f32 v117, v211, v212
	v_cvt_pk_f16_f32 v118, v213, v214
	v_pk_mul_f32 v[94:95], v[94:95], v[144:145] op_sel_hi:[1,0]
	v_pk_mul_f32 v[92:93], v[92:93], v[144:145] op_sel_hi:[1,0]
	v_cvt_pk_f16_f32 v115, v128, v130
	v_pk_mul_f32 v[102:103], v[102:103], v[120:121] op_sel_hi:[1,0]
	v_pk_mul_f32 v[100:101], v[100:101], v[120:121] op_sel_hi:[1,0]
	v_cvt_pk_f16_f32 v119, v129, v131
	v_mfma_f32_16x16x32_f16 v[92:95], v[224:227], v[112:115], v[92:95]
	v_exp_f32_e32 v139, v121
	v_pk_mul_f32 v[98:99], v[98:99], v[120:121] op_sel_hi:[1,0]
	v_pk_mul_f32 v[96:97], v[96:97], v[120:121] op_sel_hi:[1,0]
	v_mfma_f32_16x16x32_f16 v[100:103], v[224:227], v[116:119], v[100:103]
	ds_read_b128 v[224:227], v219 offset:22528
	v_sub_f32_e32 v121, v232, v143
	v_pk_mul_f32 v[90:91], v[90:91], v[120:121] op_sel_hi:[1,0]
	v_pk_mul_f32 v[88:89], v[88:89], v[120:121] op_sel_hi:[1,0]
	v_exp_f32_e32 v125, v121
	v_pk_mul_f32 v[82:83], v[82:83], v[120:121] op_sel_hi:[1,0]
	v_pk_mul_f32 v[80:81], v[80:81], v[120:121] op_sel_hi:[1,0]
	v_sub_f32_e32 v121, v233, v143
	v_sub_f32_e32 v124, v124, v141
	v_pk_mul_f32 v[74:75], v[74:75], v[120:121] op_sel_hi:[1,0]
	v_pk_mul_f32 v[72:73], v[72:73], v[120:121] op_sel_hi:[1,0]
	v_exp_f32_e32 v141, v121
	v_pk_mul_f32 v[62:63], v[62:63], v[120:121] op_sel_hi:[1,0]
	v_pk_mul_f32 v[60:61], v[60:61], v[120:121] op_sel_hi:[1,0]
	v_sub_f32_e32 v121, v234, v143
	v_exp_f32_e32 v127, v121
	v_pk_mul_f32 v[50:51], v[50:51], v[120:121] op_sel_hi:[1,0]
	v_pk_mul_f32 v[48:49], v[48:49], v[120:121] op_sel_hi:[1,0]
	v_sub_f32_e32 v121, v235, v143
	v_pk_mul_f32 v[86:87], v[86:87], v[144:145] op_sel_hi:[1,0]
	v_pk_mul_f32 v[84:85], v[84:85], v[144:145] op_sel_hi:[1,0]
	v_pk_mul_f32 v[78:79], v[78:79], v[144:145] op_sel_hi:[1,0]
	v_pk_mul_f32 v[76:77], v[76:77], v[144:145] op_sel_hi:[1,0]
	v_pk_mul_f32 v[106:107], v[106:107], v[144:145] op_sel_hi:[1,0]
	v_pk_mul_f32 v[104:105], v[104:105], v[144:145] op_sel_hi:[1,0]
	v_pk_mul_f32 v[110:111], v[110:111], v[120:121] op_sel_hi:[1,0]
	v_pk_mul_f32 v[108:109], v[108:109], v[120:121] op_sel_hi:[1,0]
	v_mfma_f32_16x16x32_f16 v[104:107], v[220:223], v[112:115], v[104:107]
	v_mul_f32_e64 v70, v70, v144
	v_mul_f32_e64 v71, v71, v144
	v_pk_mul_f32 v[68:69], v[68:69], v[144:145] op_sel_hi:[1,0]
	v_pk_mul_f32 v[58:59], v[58:59], v[144:145] op_sel_hi:[1,0]
	v_mfma_f32_16x16x32_f16 v[108:111], v[220:223], v[116:119], v[108:111]
	ds_read_b128 v[220:223], v202 offset:20480
	v_pk_mul_f32 v[56:57], v[56:57], v[144:145] op_sel_hi:[1,0]
	v_exp_f32_e32 v124, v124
	s_waitcnt lgkmcnt(2)
	v_mfma_f32_16x16x32_f16 v[84:87], v[236:239], v[112:115], v[84:87]
	v_exp_f32_e32 v143, v121
	v_pk_mul_f32 v[46:47], v[46:47], v[144:145] op_sel_hi:[1,0]
	v_pk_mul_f32 v[44:45], v[44:45], v[144:145] op_sel_hi:[1,0]
	v_mfma_f32_16x16x32_f16 v[96:99], v[236:239], v[116:119], v[96:99]
	ds_read_b128 v[236:239], v219 offset:24576
	ds_read_b128 v[240:243], v219 offset:26624
	ds_read_b128 v[244:247], v219 offset:28672
	ds_read_b128 v[248:251], v219 offset:30720
	v_pk_mul_f32 v[42:43], v[42:43], v[144:145] op_sel_hi:[1,0]
	v_pk_mul_f32 v[40:41], v[40:41], v[144:145] op_sel_hi:[1,0]
	s_waitcnt lgkmcnt(5)
	v_mfma_f32_16x16x32_f16 v[76:79], v[224:227], v[112:115], v[76:79]
	s_andn2_b64 vcc, exec, s[6:7]
	v_mfma_f32_16x16x32_f16 v[88:91], v[224:227], v[116:119], v[88:91]
	s_waitcnt lgkmcnt(3)
	v_mfma_f32_16x16x32_f16 v[68:71], v[236:239], v[112:115], v[68:71]
	v_mfma_f32_16x16x32_f16 v[80:83], v[236:239], v[116:119], v[80:83]
	s_waitcnt lgkmcnt(2)
	v_mfma_f32_16x16x32_f16 v[56:59], v[240:243], v[112:115], v[56:59]
	v_mfma_f32_16x16x32_f16 v[72:75], v[240:243], v[116:119], v[72:75]
	s_waitcnt lgkmcnt(1)
	v_mfma_f32_16x16x32_f16 v[44:47], v[244:247], v[112:115], v[44:47]
	v_mfma_f32_16x16x32_f16 v[60:63], v[244:247], v[116:119], v[60:63]
	s_waitcnt lgkmcnt(0)
	v_mfma_f32_16x16x32_f16 v[40:43], v[248:251], v[112:115], v[40:43]
	v_cvt_pk_f16_f32 v112, v133, v137
	v_cvt_pk_f16_f32 v113, v135, v139
	v_cvt_pk_f16_f32 v114, v125, v141
	v_mfma_f32_16x16x32_f16 v[48:51], v[248:251], v[116:119], v[48:51]
	v_cvt_pk_f16_f32 v116, v132, v136
	v_cvt_pk_f16_f32 v117, v134, v138
	v_cvt_pk_f16_f32 v118, v124, v140
	v_cvt_pk_f16_f32 v119, v126, v142
	v_cvt_pk_f16_f32 v115, v127, v143
	s_nop 0
	v_mfma_f32_16x16x32_f16 v[84:87], v[220:223], v[116:119], v[84:87]
	v_mfma_f32_16x16x32_f16 v[96:99], v[220:223], v[112:115], v[96:99]
	ds_read_b128 v[220:223], v202 offset:22528
	ds_read_b128 v[240:243], v202 offset:24576
	ds_read_b128 v[244:247], v202 offset:26624
	ds_read_b128 v[248:251], v202 offset:28672
	s_waitcnt lgkmcnt(3)
	v_mfma_f32_16x16x32_f16 v[76:79], v[220:223], v[116:119], v[76:79]
	v_mfma_f32_16x16x32_f16 v[88:91], v[220:223], v[112:115], v[88:91]
	ds_read_b128 v[220:223], v202 offset:30720
	s_waitcnt lgkmcnt(3)
	v_mfma_f32_16x16x32_f16 v[68:71], v[240:243], v[116:119], v[68:71]
	v_mfma_f32_16x16x32_f16 v[80:83], v[240:243], v[112:115], v[80:83]
	ds_read_b128 v[240:243], v202 offset:32768
	s_waitcnt lgkmcnt(3)
	v_mfma_f32_16x16x32_f16 v[56:59], v[244:247], v[116:119], v[56:59]
	v_mfma_f32_16x16x32_f16 v[72:75], v[244:247], v[112:115], v[72:75]
	s_waitcnt lgkmcnt(2)
	v_mfma_f32_16x16x32_f16 v[44:47], v[248:251], v[116:119], v[44:47]
	v_mfma_f32_16x16x32_f16 v[60:63], v[248:251], v[112:115], v[60:63]
	s_waitcnt lgkmcnt(1)
	v_mfma_f32_16x16x32_f16 v[40:43], v[220:223], v[116:119], v[40:43]
	v_mfma_f32_16x16x32_f16 v[48:51], v[220:223], v[112:115], v[48:51]
	v_mfma_f32_16x16x32_f16 v[92:95], v[228:231], v[116:119], v[92:95]
	v_mfma_f32_16x16x32_f16 v[100:103], v[228:231], v[112:115], v[100:103]
	s_waitcnt lgkmcnt(0)
	v_mfma_f32_16x16x32_f16 v[104:107], v[240:243], v[116:119], v[104:107]
	v_mfma_f32_16x16x32_f16 v[108:111], v[240:243], v[112:115], v[108:111]
	s_cbranch_vccnz .LBB0_807
; DI void st_chunk_v(char* sdst, int c, const uint4& v) {
;   const int row = c >> 3, c8 = c & 7, kk = c8 >> 2, cc = c8 & 3, sw = (row >> 1) & 7;
;   const int gq = (cc & 1) * 2, part = cc >> 1;
;   char* base = sdst + row * 128 + part * 8;
;   *(uint2*)(base + (((kk * 4 + gq) ^ sw) << 4)) = make_uint2(v.x, v.y);
;   *(uint2*)(base + (((kk * 4 + gq + 1) ^ sw) << 4)) = make_uint2(v.z, v.w);
; }
; DI void gload2(R2& r, const bf16_t* gsrc, size_t gp, int tid) { r.a = ld_chunk(gsrc, gp, tid); r.b = ld_chunk(gsrc, gp, tid + 256); }
; DI void gload4(R4& r, const bf16_t* gsrc, size_t gp, int tid) { r.a = ld_chunk(gsrc, gp, tid); r.b = ld_chunk(gsrc, gp, tid + 256); r.c = ld_chunk(gsrc, gp, tid + 512); r.d = ld_chunk(gsrc, gp, tid + 768); }
; DI void sstoreK2(const R2& r, char* sdst, int tid) { st_chunk_k(sdst, tid, r.a); st_chunk_k(sdst, tid + 256, r.b); }
; DI void sstoreV2(const R2& r, char* sdst, int tid) { st_chunk_v(sdst, tid, r.a); st_chunk_v(sdst, tid + 256, r.b); }
; DI void sstoreV4(const R4& r, char* sdst, int tid) { st_chunk_v(sdst, tid, r.a); st_chunk_v(sdst, tid + 256, r.b); st_chunk_v(sdst, tid + 512, r.c); st_chunk_v(sdst, tid + 768, r.d); }
; DI void attn_A(const Params& P, int l, int b, int head, int qt, float lam, char* smem, bf16_t* ybase, size_t ypitch) {
;     ...
;     if (n < qt) {
;       char* sn = smem + ((n + 1) & 1) * STAGE;
;       sstoreK2(rk0, sn, tid); sstoreK2(rk1, sn + 9216, tid); sstoreV4(rv, sn + 18432, tid);
;     }
;     __syncthreads();
	s_andn2_b32 s6, 1, s8
	s_mul_i32 s6, s6, 0x9000
	v_add_u32_e32 v112, s6, v155
	v_add_u32_e32 v113, v112, v195
	v_add_u32_e32 v112, v112, v196
	s_waitcnt vmcnt(7)
	ds_write_b128 v113, v[16:19]
	s_waitcnt vmcnt(5)
	ds_write_b128 v113, v[20:23] offset:4096
	ds_write_b128 v113, v[24:27] offset:9216
	s_waitcnt vmcnt(4)
	ds_write_b128 v113, v[28:31] offset:13312
	v_add_u32_e32 v113, v112, v197
	v_add_u32_e32 v112, v112, v198
	s_waitcnt vmcnt(2)
	ds_write2st64_b64 v113, v[32:33], v[36:37] offset0:36 offset1:44
	ds_write2st64_b64 v112, v[34:35], v[38:39] offset0:36 offset1:44
	s_waitcnt vmcnt(0)
	ds_write2st64_b64 v113, v[52:53], v[64:65] offset0:52 offset1:60
	ds_write2st64_b64 v112, v[54:55], v[66:67] offset0:52 offset1:60
	s_branch .LBB0_807
